# attention unit prologues: MLA tile-1 K loads join tile 0's under one wait; NATTEN tile-0 K/V loads issued before the bias-table fill
# speedup vs baseline: 1.0025x; 1.0025x over previous
.LBB0_1084:
	s_andn2_saveexec_b64 s[64:65], s[64:65]
	s_cbranch_execz .LBB0_1145
	v_mov_b32_e32 v33, v246
	v_mov_b32_e32 v35, v113
	v_ashrrev_i32_e32 v38, 1, v33
	v_bfe_u32 v36, v33, 5, 1
	v_bfi_b32 v2, s92, v38, v33
	v_mad_i64_i32 v[166:167], s[2:3], v2, s33, v[0:1]
	v_lshlrev_b32_e32 v34, 4, v36
	v_lshl_add_u64 v[0:1], v[166:167], 0, v[34:35]
	s_waitcnt vmcnt(0)
	global_load_dwordx4 v[114:117], v[0:1], off offset:3072
	global_load_dwordx4 v[118:121], v[0:1], off offset:3104
	global_load_dwordx4 v[122:125], v[0:1], off offset:3136
	global_load_dwordx4 v[126:129], v[0:1], off offset:3168
	v_ashrrev_i32_e32 v0, 31, v33
	v_lshrrev_b32_e32 v0, 29, v0
	v_add_u32_e32 v0, v33, v0
	v_ashrrev_i32_e32 v1, 3, v0
	v_and_b32_e32 v0, -8, v0
	v_sub_u32_e32 v174, 0, v201
	v_cmp_lt_i32_e32 vcc, 0, v201
	v_sub_u32_e32 v6, v33, v0
	v_ashrrev_i32_e32 v7, 3, v33
	v_cndmask_b32_e32 v3, v163, v141, vcc
	v_cndmask_b32_e32 v2, v162, v140, vcc
	v_cndmask_b32_e32 v9, v174, v164, vcc
	v_cndmask_b32_e32 v5, v145, v139, vcc
	v_cndmask_b32_e32 v4, v144, v138, vcc
	s_movk_i32 s6, 0x1b00
	v_and_b32_e32 v0, 7, v33
	v_mad_u64_u32 v[4:5], s[2:3], v9, s74, v[4:5]
	v_mad_i64_i32 v[168:169], s[2:3], v1, s6, 0
	v_lshlrev_b32_e32 v170, 3, v6
	v_mad_u64_u32 v[2:3], s[2:3], v9, s74, v[2:3]
	v_mad_i64_i32 v[172:173], s[2:3], v7, s6, 0
	v_lshl_add_u64 v[4:5], v[168:169], 1, v[4:5]
	v_ashrrev_i32_e32 v171, 31, v170
	v_lshl_add_u64 v[2:3], v[172:173], 1, v[2:3]
	v_lshlrev_b32_e32 v112, 4, v0
	v_lshl_add_u64 v[4:5], v[170:171], 1, v[4:5]
	v_lshl_add_u64 v[2:3], v[2:3], 0, v[112:113]
	global_load_dwordx4 v[130:133], v[4:5], off
	global_load_dwordx4 v[134:137], v[2:3], off
	s_movk_i32 s2, 0x1e0
	v_and_b32_e32 v32, 31, v33
	v_cmp_gt_i32_e32 vcc, s2, v33
	s_and_saveexec_b64 s[2:3], vcc
	s_cbranch_execz .LBB0_1090
	v_readlane_b32 s6, v254, 34
	v_cmp_ne_u32_e32 vcc, 31, v32
	s_mov_b64 s[8:9], 0
	v_lshl_add_u32 v0, v33, 2, s6
	v_mov_b32_e32 v1, v33
	s_branch .LBB0_1088

.LBB0_1090:
	s_or_b64 exec, exec, s[2:3]
	v_ashrrev_i32_e32 v0, 31, v33
	v_lshrrev_b32_e32 v0, 29, v0
	v_add_u32_e32 v0, v33, v0
	v_ashrrev_i32_e32 v1, 3, v0
	v_and_b32_e32 v0, 7, v33
	v_mul_lo_u32 v2, v7, s20
	v_add3_u32 v203, 0, v2, v112
	v_mul_lo_u32 v1, v1, s20
	v_lshlrev_b32_e32 v2, 4, v6
	v_and_b32_e32 v202, 63, v33
	v_cmp_gt_i32_e32 vcc, 1, v201
	v_add3_u32 v204, 0, v1, v2
	v_cmp_lt_i32_e64 s[6:7], 1, v142
	s_waitcnt vmcnt(0) lgkmcnt(0)
	ds_write_b128 v204, v[130:133]
	ds_write_b128 v203, v[134:137] offset:26624
	s_and_saveexec_b64 s[2:3], s[6:7]
	s_cbranch_execz .LBB0_1092
	v_cmp_lt_i32_e64 s[8:9], 1, v201
	s_nop 1
	v_cndmask_b32_e64 v1, v174, v164, s[8:9]
	v_add_u32_e32 v1, 1, v1
	v_cndmask_b32_e64 v3, v145, v139, s[8:9]
	v_cndmask_b32_e64 v2, v144, v138, s[8:9]
	v_mad_u64_u32 v[2:3], s[8:9], v1, s74, v[2:3]
	v_lshl_add_u64 v[2:3], v[168:169], 1, v[2:3]
	v_lshl_add_u64 v[2:3], v[170:171], 1, v[2:3]
	global_load_dwordx4 v[130:133], v[2:3], off
	s_waitcnt vmcnt(0) lgkmcnt(0)
	ds_write_b128 v204, v[130:133] offset:13312

.LBB0_1176:
	s_or_b64 exec, exec, s[2:3]
	v_ashrrev_i32_e32 v24, 3, v29
	v_ashrrev_i32_e32 v25, 31, v24
	v_and_b32_e32 v32, 7, v29
	v_lshlrev_b64 v[20:21], 7, v[24:25]
	v_lshl_add_u64 v[4:5], v[12:13], 0, v[20:21]
	v_lshlrev_b32_e32 v112, 4, v32
	v_lshl_add_u64 v[140:141], v[4:5], 0, v[112:113]
	global_load_dwordx4 v[4:7], v[140:141], off
	v_lshl_add_u64 v[232:233], v[14:15], 0, s[24:25]
	v_lshl_add_u64 v[230:231], v[26:27], 1, v[232:233]
	v_lshl_add_u64 v[230:231], v[16:17], 1, v[230:231]
	global_load_dwordx4 v[128:131], v[230:231], off
	s_and_saveexec_b64 s[2:3], s[6:7]
	s_cbranch_execz .Lmla_pro_k1
	v_mad_i64_i32 v[230:231], s[18:19], v31, s22, v[232:233]
	v_lshl_add_u64 v[230:231], v[18:19], 1, v[230:231]
	global_load_dwordx4 v[132:135], v[230:231], off
.Lmla_pro_k1:
	s_or_b64 exec, exec, s[2:3]
	s_movk_i32 s2, 0xd0
	v_mul_lo_u32 v168, v23, s2
	v_add_u32_e32 v35, 0, v168
	v_lshlrev_b32_e32 v170, 4, v33
	v_mul_lo_u32 v171, v31, s2
	v_lshlrev_b32_e32 v172, 4, v34
	v_add_u32_e32 v169, v35, v170
	v_add3_u32 v167, 0, v171, v172
	s_waitcnt vmcnt(0) lgkmcnt(0)
	ds_write_b128 v169, v[0:3]
	s_and_saveexec_b64 s[2:3], s[6:7]
	ds_write_b128 v167, v[124:127]
	s_or_b64 exec, exec, s[2:3]
	v_mul_lo_u32 v0, v24, s20
	v_add3_u32 v115, 0, v0, v112
	ds_write_b128 v115, v[4:7] offset:26624
	ds_write_b128 v169, v[128:131] offset:13312
	s_and_saveexec_b64 s[2:3], s[6:7]
	ds_write_b128 v167, v[132:135] offset:13312
	s_or_b64 exec, exec, s[2:3]
	s_mov_b64 s[2:3], 0x6000
	v_lshl_add_u64 v[2:3], v[14:15], 0, s[2:3]
	v_lshl_add_u64 v[0:1], v[26:27], 1, v[2:3]
	v_lshl_add_u64 v[0:1], v[16:17], 1, v[0:1]
	global_load_dwordx4 v[128:131], v[0:1], off
	s_and_saveexec_b64 s[2:3], vcc
	s_xor_b64 s[2:3], exec, s[2:3]
	v_mad_u64_u32 v[0:1], s[18:19], v31, s22, 0
	v_mov_b32_e32 v19, v113
	s_andn2_saveexec_b64 s[2:3], s[2:3]
	s_cbranch_execz .LBB0_1186
	v_mad_i64_i32 v[0:1], s[18:19], v31, s22, v[2:3]
	v_lshl_add_u64 v[0:1], v[18:19], 1, v[0:1]
	global_load_dwordx4 v[124:127], v[0:1], off
	v_mad_i64_i32 v[0:1], s[18:19], v31, s22, 0
